# DF epilogue store section regenerated 4-way interleaved on scratch registers (g loads hoisted); otherwise as previous best
# speedup vs baseline: 1.0253x; 1.0014x over previous
; template <bool FIXED>
; __device__ __forceinline__ void df_unit(LAS char* lds, bf16_t* QKV, const float* gsub, float lam, float post, int b, int h, int qb, int wave0, float mfix2) {
;     ...
;     __syncthreads();
;     if (mp == 0) {
;         float ssq[16];
; #pragma unroll
;         for (int r = 0; r < 16; ++r) ssq[r] = 0.f;
; #pragma unroll
;         for (int d = 0; d < 8; ++d)
; #pragma unroll
;             for (int r = 0; r < 16; ++r) { const float v = o[d][r] * rli[r] - xch[(d * 16 + r) * 64]; o[d][r] = v; ssq[r] += v * v; }
.LBB0_154:
	s_cmpk_gt_u32 s16, 0xff
	s_waitcnt lgkmcnt(0)
	s_barrier
	s_cbranch_scc1 .LBB0_156
	ds_read2st64_b32 v[180:181], v174 offset1:1
	ds_read2st64_b32 v[182:183], v174 offset0:10 offset1:11
	ds_read2st64_b32 v[184:185], v174 offset0:2 offset1:3
	ds_read2st64_b32 v[186:187], v174 offset0:4 offset1:5
	ds_read2st64_b32 v[188:189], v174 offset0:6 offset1:7
	ds_read2st64_b32 v[190:191], v174 offset0:8 offset1:9
	ds_read2st64_b32 v[192:193], v174 offset0:12 offset1:13
	ds_read2st64_b32 v[194:195], v174 offset0:14 offset1:15
	ds_read2st64_b32 v[196:197], v174 offset0:16 offset1:17
	ds_read2st64_b32 v[198:199], v174 offset0:18 offset1:19
	ds_read2st64_b32 v[200:201], v174 offset0:20 offset1:21
	ds_read2st64_b32 v[206:207], v174 offset0:22 offset1:23
	ds_read2st64_b32 v[208:209], v174 offset0:24 offset1:25
	ds_read2st64_b32 v[210:211], v174 offset0:26 offset1:27
	s_movk_i32 s0, 0x6000
	s_waitcnt lgkmcnt(13)
	v_fma_f32 v135, v114, v0, -v180
	v_fma_f32 v131, v115, v136, -v181
	ds_read2st64_b32 v[212:213], v174 offset0:28 offset1:29
	s_waitcnt lgkmcnt(12)
	v_fma_f32 v132, v116, v137, -v184
	v_fma_f32 v117, v117, v138, -v185
	ds_read2st64_b32 v[214:215], v174 offset0:30 offset1:31
	s_waitcnt lgkmcnt(12)
	v_fma_f32 v130, v118, v139, -v186
	v_fma_f32 v115, v119, v141, -v187
	ds_read2st64_b32 v[218:219], v174 offset0:32 offset1:33
	s_waitcnt lgkmcnt(12)
	v_fma_f32 v134, v120, v140, -v188
	v_fma_f32 v119, v121, v142, -v189
	ds_read2st64_b32 v[220:221], v174 offset0:34 offset1:35
	v_fma_f32 v118, v125, v145, -v183
	s_waitcnt lgkmcnt(12)
	v_fma_f32 v133, v122, v144, -v190
	v_fma_f32 v120, v123, v146, -v191
	v_fma_f32 v123, v124, v143, -v182
	ds_read2st64_b32 v[226:227], v174 offset0:36 offset1:37
	s_waitcnt lgkmcnt(12)
	v_fma_f32 v122, v126, v167, -v192
	v_fma_f32 v116, v127, v169, -v193
	ds_read2st64_b32 v[228:229], v174 offset0:38 offset1:39
	ds_read2st64_b32 v[234:235], v174 offset0:40 offset1:41
	s_waitcnt lgkmcnt(13)
	v_fma_f32 v121, v129, v173, -v195
	s_waitcnt lgkmcnt(12)
	v_fma_f32 v114, v98, v0, -v196
	v_fma_f32 v98, v99, v136, -v197
	ds_read2st64_b32 v[236:237], v174 offset0:42 offset1:43
	v_fma_f32 v124, v128, v170, -v194
	v_mul_f32_e32 v179, v114, v114
	v_fmac_f32_e32 v179, v135, v135
	v_mul_f32_e32 v178, v98, v98
	s_waitcnt lgkmcnt(12)
	v_fma_f32 v100, v100, v137, -v198
	v_fma_f32 v99, v101, v138, -v199
	ds_read2st64_b32 v[238:239], v174 offset0:44 offset1:45
	v_fmac_f32_e32 v178, v131, v131
	v_mul_f32_e32 v177, v100, v100
	v_fmac_f32_e32 v177, v132, v132
	v_mul_f32_e32 v176, v99, v99
	s_waitcnt lgkmcnt(12)
	v_fma_f32 v102, v102, v139, -v200
	v_fma_f32 v101, v103, v141, -v201
	ds_read2st64_b32 v[240:241], v174 offset0:46 offset1:47
	v_fmac_f32_e32 v176, v117, v117
	v_mul_f32_e32 v175, v102, v102
	v_fmac_f32_e32 v175, v130, v130
	v_mul_f32_e32 v171, v101, v101
	s_waitcnt lgkmcnt(12)
	v_fma_f32 v104, v104, v140, -v206
	v_fma_f32 v103, v105, v142, -v207
	ds_read2st64_b32 v[242:243], v174 offset0:48 offset1:49
	v_fmac_f32_e32 v171, v115, v115
	v_mul_f32_e32 v172, v104, v104
	v_fmac_f32_e32 v172, v134, v134
	v_mul_f32_e32 v168, v103, v103
	s_waitcnt lgkmcnt(12)
	v_fma_f32 v106, v106, v144, -v208
	v_fma_f32 v105, v107, v146, -v209
	ds_read2st64_b32 v[244:245], v174 offset0:50 offset1:51
	v_fmac_f32_e32 v168, v119, v119
	v_mul_f32_e32 v166, v106, v106
	v_fmac_f32_e32 v166, v133, v133
	v_mul_f32_e32 v161, v105, v105
	s_waitcnt lgkmcnt(12)
	v_fma_f32 v108, v108, v143, -v210
	v_fma_f32 v107, v109, v145, -v211
	ds_read2st64_b32 v[246:247], v174 offset0:52 offset1:53
	v_fmac_f32_e32 v161, v120, v120
	v_mul_f32_e32 v154, v108, v108
	v_fmac_f32_e32 v154, v123, v123
	v_mul_f32_e32 v147, v107, v107
	s_waitcnt lgkmcnt(12)
	v_fma_f32 v110, v110, v167, -v212
	v_fma_f32 v109, v111, v169, -v213
	ds_read2st64_b32 v[248:249], v174 offset0:54 offset1:55
	v_fmac_f32_e32 v147, v118, v118
	v_mul_f32_e32 v149, v110, v110
	v_fmac_f32_e32 v149, v122, v122
	v_mul_f32_e32 v148, v109, v109
	s_waitcnt lgkmcnt(12)
	v_fma_f32 v112, v112, v170, -v214
	v_fma_f32 v113, v113, v173, -v215
	ds_read2st64_b32 v[180:181], v174 offset0:56 offset1:57
	v_fmac_f32_e32 v148, v116, v116
	v_mul_f32_e32 v158, v112, v112
	v_fmac_f32_e32 v158, v124, v124
	v_mul_f32_e32 v156, v113, v113
	s_waitcnt lgkmcnt(12)
	v_fma_f32 v111, v82, v0, -v218
	v_fma_f32 v82, v83, v136, -v219
	ds_read2st64_b32 v[184:185], v174 offset0:58 offset1:59
	v_fmac_f32_e32 v179, v111, v111
	v_fmac_f32_e32 v178, v82, v82
	v_fmac_f32_e32 v156, v121, v121
	s_waitcnt lgkmcnt(12)
	v_fma_f32 v84, v84, v137, -v220
	v_fma_f32 v83, v85, v138, -v221
	ds_read2st64_b32 v[186:187], v174 offset0:60 offset1:61
	v_fmac_f32_e32 v177, v84, v84
	v_fmac_f32_e32 v176, v83, v83
	s_waitcnt lgkmcnt(12)
	v_fma_f32 v86, v86, v139, -v226
	v_fma_f32 v85, v87, v141, -v227
	ds_read2st64_b32 v[188:189], v174 offset0:62 offset1:63
	v_fmac_f32_e32 v175, v86, v86
	v_fmac_f32_e32 v171, v85, v85
	s_waitcnt lgkmcnt(12)
	v_fma_f32 v88, v88, v140, -v228
	v_fma_f32 v87, v89, v142, -v229
	ds_read2st64_b32 v[190:191], v174 offset0:64 offset1:65
	v_fmac_f32_e32 v172, v88, v88
	v_fmac_f32_e32 v168, v87, v87
	s_waitcnt lgkmcnt(12)
	v_fma_f32 v90, v90, v144, -v234
	v_fma_f32 v89, v91, v146, -v235
	ds_read2st64_b32 v[182:183], v174 offset0:66 offset1:67
	v_fmac_f32_e32 v166, v90, v90
	v_fmac_f32_e32 v161, v89, v89
	s_waitcnt lgkmcnt(12)
	v_fma_f32 v92, v92, v143, -v236
	v_fma_f32 v91, v93, v145, -v237
	ds_read2st64_b32 v[192:193], v174 offset0:68 offset1:69
	v_fmac_f32_e32 v154, v92, v92
	v_fmac_f32_e32 v147, v91, v91
	s_waitcnt lgkmcnt(12)
	v_fma_f32 v94, v94, v167, -v238
	v_fma_f32 v93, v95, v169, -v239
	ds_read2st64_b32 v[196:197], v174 offset0:70 offset1:71
	v_fmac_f32_e32 v149, v94, v94
	v_fmac_f32_e32 v148, v93, v93
	s_waitcnt lgkmcnt(12)
; template <bool FIXED>
; __device__ __forceinline__ void df_unit(LAS char* lds, bf16_t* QKV, const float* gsub, float lam, float post, int b, int h, int qb, int wave0, float mfix2) {
;     ...
;         for (int d = 0; d < 8; ++d)
; #pragma unroll
;             for (int r = 0; r < 16; ++r) { const float v = o[d][r] * rli[r] - xch[(d * 16 + r) * 64]; o[d][r] = v; ssq[r] += v * v; }
	v_fma_f32 v125, v96, v170, -v240
	v_fma_f32 v96, v97, v173, -v241
	ds_read2st64_b32 v[194:195], v174 offset0:72 offset1:73
	v_fmac_f32_e32 v158, v125, v125
	v_fmac_f32_e32 v156, v96, v96
	s_waitcnt lgkmcnt(12)
	v_fma_f32 v95, v66, v0, -v242
	v_fma_f32 v66, v67, v136, -v243
	ds_read2st64_b32 v[198:199], v174 offset0:74 offset1:75
	v_fmac_f32_e32 v179, v95, v95
	v_fmac_f32_e32 v178, v66, v66
	s_waitcnt lgkmcnt(12)
	v_fma_f32 v68, v68, v137, -v244
	v_fma_f32 v67, v69, v138, -v245
	ds_read2st64_b32 v[200:201], v174 offset0:76 offset1:77
	v_fmac_f32_e32 v177, v68, v68
	v_fmac_f32_e32 v176, v67, v67
	s_waitcnt lgkmcnt(12)
	v_fma_f32 v70, v70, v139, -v246
	v_fma_f32 v69, v71, v141, -v247
	ds_read2st64_b32 v[206:207], v174 offset0:78 offset1:79
	v_fmac_f32_e32 v175, v70, v70
	v_fmac_f32_e32 v171, v69, v69
	s_waitcnt lgkmcnt(12)
	v_fma_f32 v72, v72, v140, -v248
	v_fma_f32 v71, v73, v142, -v249
	ds_read2st64_b32 v[208:209], v174 offset0:80 offset1:81
	v_fmac_f32_e32 v172, v72, v72
	v_fmac_f32_e32 v168, v71, v71
	s_waitcnt lgkmcnt(12)
	v_fma_f32 v74, v74, v144, -v180
	v_fma_f32 v73, v75, v146, -v181
	ds_read2st64_b32 v[210:211], v174 offset0:82 offset1:83
	v_fmac_f32_e32 v166, v74, v74
	v_fmac_f32_e32 v161, v73, v73
	s_waitcnt lgkmcnt(12)
	v_fma_f32 v76, v76, v143, -v184
	v_fma_f32 v75, v77, v145, -v185
	ds_read2st64_b32 v[212:213], v174 offset0:84 offset1:85
	v_fmac_f32_e32 v154, v76, v76
	v_fmac_f32_e32 v147, v75, v75
	s_waitcnt lgkmcnt(12)
	v_fma_f32 v78, v78, v167, -v186
	v_fma_f32 v77, v79, v169, -v187
	ds_read2st64_b32 v[214:215], v174 offset0:86 offset1:87
	v_fmac_f32_e32 v149, v78, v78
	v_fmac_f32_e32 v148, v77, v77
	s_waitcnt lgkmcnt(12)
	v_fma_f32 v97, v80, v170, -v188
	v_fma_f32 v80, v81, v173, -v189
	ds_read2st64_b32 v[218:219], v174 offset0:88 offset1:89
	v_fmac_f32_e32 v158, v97, v97
	v_fmac_f32_e32 v156, v80, v80
	s_waitcnt lgkmcnt(12)
	v_fma_f32 v79, v50, v0, -v190
	v_fma_f32 v50, v51, v136, -v191
	ds_read2st64_b32 v[220:221], v174 offset0:90 offset1:91
	v_fmac_f32_e32 v179, v79, v79
	v_fmac_f32_e32 v178, v50, v50
	s_waitcnt lgkmcnt(12)
	v_fma_f32 v52, v52, v137, -v182
	v_fma_f32 v51, v53, v138, -v183
	ds_read2st64_b32 v[226:227], v174 offset0:92 offset1:93
	v_fmac_f32_e32 v177, v52, v52
	v_fmac_f32_e32 v176, v51, v51
	s_waitcnt lgkmcnt(12)
	v_fma_f32 v54, v54, v139, -v192
	v_fma_f32 v53, v55, v141, -v193
	ds_read2st64_b32 v[228:229], v174 offset0:94 offset1:95
	v_fmac_f32_e32 v175, v54, v54
	v_fmac_f32_e32 v171, v53, v53
	s_waitcnt lgkmcnt(12)
	v_fma_f32 v56, v56, v140, -v196
	v_fma_f32 v55, v57, v142, -v197
	ds_read2st64_b32 v[234:235], v174 offset0:96 offset1:97
	v_fmac_f32_e32 v172, v56, v56
	v_fmac_f32_e32 v168, v55, v55
	s_waitcnt lgkmcnt(12)
	v_fma_f32 v58, v58, v144, -v194
	v_fma_f32 v57, v59, v146, -v195
	ds_read2st64_b32 v[236:237], v174 offset0:98 offset1:99
	v_fmac_f32_e32 v166, v58, v58
	v_fmac_f32_e32 v161, v57, v57
	s_waitcnt lgkmcnt(12)
	v_fma_f32 v60, v60, v143, -v198
	v_fma_f32 v59, v61, v145, -v199
	ds_read2st64_b32 v[238:239], v174 offset0:100 offset1:101
	v_fmac_f32_e32 v154, v60, v60
	v_fmac_f32_e32 v147, v59, v59
	s_waitcnt lgkmcnt(12)
	v_fma_f32 v62, v62, v167, -v200
	v_fma_f32 v61, v63, v169, -v201
	ds_read2st64_b32 v[240:241], v174 offset0:102 offset1:103
	v_fmac_f32_e32 v149, v62, v62
	v_fmac_f32_e32 v148, v61, v61
	s_waitcnt lgkmcnt(12)
	v_fma_f32 v81, v64, v170, -v206
	v_fma_f32 v64, v65, v173, -v207
	ds_read2st64_b32 v[242:243], v174 offset0:104 offset1:105
	v_fmac_f32_e32 v158, v81, v81
	v_fmac_f32_e32 v156, v64, v64
	s_waitcnt lgkmcnt(12)
	v_fma_f32 v63, v34, v0, -v208
	v_fma_f32 v34, v35, v136, -v209
	ds_read2st64_b32 v[244:245], v174 offset0:106 offset1:107
	v_fmac_f32_e32 v179, v63, v63
	v_fmac_f32_e32 v178, v34, v34
	s_waitcnt lgkmcnt(12)
	v_fma_f32 v36, v36, v137, -v210
	v_fma_f32 v35, v37, v138, -v211
	ds_read2st64_b32 v[246:247], v174 offset0:108 offset1:109
	v_fmac_f32_e32 v177, v36, v36
	v_fmac_f32_e32 v176, v35, v35
	s_waitcnt lgkmcnt(12)
	v_fma_f32 v38, v38, v139, -v212
	v_fma_f32 v37, v39, v141, -v213
	ds_read2st64_b32 v[248:249], v174 offset0:110 offset1:111
	v_fmac_f32_e32 v175, v38, v38
	v_fmac_f32_e32 v171, v37, v37
	s_waitcnt lgkmcnt(12)
	v_fma_f32 v40, v40, v140, -v214
	v_fma_f32 v39, v41, v142, -v215
	ds_read2st64_b32 v[180:181], v174 offset0:112 offset1:113
	v_fmac_f32_e32 v172, v40, v40
	v_fmac_f32_e32 v168, v39, v39
	s_waitcnt lgkmcnt(12)
	v_fma_f32 v42, v42, v144, -v218
	v_fma_f32 v41, v43, v146, -v219
	ds_read2st64_b32 v[184:185], v174 offset0:114 offset1:115
	v_fmac_f32_e32 v166, v42, v42
	v_fmac_f32_e32 v161, v41, v41
	s_waitcnt lgkmcnt(12)
	v_fma_f32 v44, v44, v143, -v220
	v_fma_f32 v43, v45, v145, -v221
	ds_read2st64_b32 v[186:187], v174 offset0:116 offset1:117
	v_fmac_f32_e32 v154, v44, v44
	v_fmac_f32_e32 v147, v43, v43
	s_waitcnt lgkmcnt(12)
	v_fma_f32 v46, v46, v167, -v226
	v_fma_f32 v45, v47, v169, -v227
	ds_read2st64_b32 v[188:189], v174 offset0:118 offset1:119
	v_fmac_f32_e32 v149, v46, v46
	v_fmac_f32_e32 v148, v45, v45
	s_waitcnt lgkmcnt(12)
	v_fma_f32 v65, v48, v170, -v228
	v_fma_f32 v49, v49, v173, -v229
	ds_read2st64_b32 v[190:191], v174 offset0:120 offset1:121
	v_fmac_f32_e32 v158, v65, v65
	v_fmac_f32_e32 v156, v49, v49
	s_waitcnt lgkmcnt(12)
	v_fma_f32 v48, v18, v0, -v234
	v_fma_f32 v47, v19, v136, -v235
	ds_read2st64_b32 v[182:183], v174 offset0:122 offset1:123
	v_fmac_f32_e32 v179, v48, v48
	v_fmac_f32_e32 v178, v47, v47
	s_waitcnt lgkmcnt(12)
	v_fma_f32 v127, v20, v137, -v236
	v_fma_f32 v126, v21, v138, -v237
	ds_read2st64_b32 v[192:193], v174 offset0:124 offset1:125
	v_fmac_f32_e32 v177, v127, v127
	v_fmac_f32_e32 v176, v126, v126
	s_waitcnt lgkmcnt(12)
; template <bool FIXED>
; __device__ __forceinline__ void df_unit(LAS char* lds, bf16_t* QKV, const float* gsub, float lam, float post, int b, int h, int qb, int wave0, float mfix2) {
;     ...
;         for (int d = 0; d < 8; ++d)
; #pragma unroll
;             for (int r = 0; r < 16; ++r) { const float v = o[d][r] * rli[r] - xch[(d * 16 + r) * 64]; o[d][r] = v; ssq[r] += v * v; }
; #pragma unroll
;         for (int r = 0; r < 16; ++r) { float s = ssq[r]; s = xsum<1>(s); s = xsum<2>(s); s = xsum<4>(s); s = xsum<8>(s); s = xsum<16>(s);
	v_fma_f32 v129, v22, v139, -v238
	v_fma_f32 v128, v23, v141, -v239
	ds_read2st64_b32 v[196:197], v174 offset0:126 offset1:127
	v_fmac_f32_e32 v175, v129, v129
	v_fmac_f32_e32 v171, v128, v128
	s_waitcnt lgkmcnt(12)
	v_fma_f32 v151, v24, v140, -v240
	v_fma_f32 v150, v25, v142, -v241
	v_fmac_f32_e32 v172, v151, v151
	v_fmac_f32_e32 v168, v150, v150
	s_waitcnt lgkmcnt(11)
	v_fma_f32 v153, v26, v144, -v242
	v_fma_f32 v152, v27, v146, -v243
	v_fmac_f32_e32 v166, v153, v153
	v_fmac_f32_e32 v161, v152, v152
	s_waitcnt lgkmcnt(10)
	v_fma_f32 v157, v28, v143, -v244
	v_fma_f32 v155, v29, v145, -v245
	v_fmac_f32_e32 v154, v157, v157
	v_fmac_f32_e32 v147, v155, v155
	s_waitcnt lgkmcnt(9)
	v_fma_f32 v160, v30, v167, -v246
	v_fma_f32 v159, v31, v169, -v247
	v_fmac_f32_e32 v149, v160, v160
	v_fmac_f32_e32 v148, v159, v159
	s_waitcnt lgkmcnt(8)
	v_fma_f32 v164, v32, v170, -v248
	v_fma_f32 v163, v33, v173, -v249
	v_fmac_f32_e32 v158, v164, v164
	v_fmac_f32_e32 v156, v163, v163
	s_waitcnt lgkmcnt(7)
	v_fma_f32 v162, v2, v0, -v180
	v_fma_f32 v136, v3, v136, -v181
	v_fmac_f32_e32 v179, v162, v162
	v_fmac_f32_e32 v178, v136, v136
	v_mov_b32_e32 v19, v1
	s_waitcnt lgkmcnt(6)
	v_fma_f32 v165, v4, v137, -v184
	v_fma_f32 v137, v5, v138, -v185
	v_fmac_f32_e32 v177, v165, v165
	v_fmac_f32_e32 v176, v137, v137
	s_waitcnt lgkmcnt(5)
	v_fma_f32 v139, v6, v139, -v186
	v_fma_f32 v138, v7, v141, -v187
	v_fmac_f32_e32 v175, v139, v139
	v_fmac_f32_e32 v171, v138, v138
	v_mov_b32_e32 v7, v1
	s_waitcnt lgkmcnt(4)
	v_fma_f32 v141, v8, v140, -v188
	v_fma_f32 v140, v9, v142, -v189
	v_fmac_f32_e32 v172, v141, v141
	v_fmac_f32_e32 v168, v140, v140
	s_waitcnt lgkmcnt(3)
	v_fma_f32 v144, v10, v144, -v190
	v_fma_f32 v142, v11, v146, -v191
	v_fmac_f32_e32 v166, v144, v144
	v_fmac_f32_e32 v161, v142, v142
	s_waitcnt lgkmcnt(2)
	v_fma_f32 v146, v12, v143, -v182
	v_fma_f32 v143, v13, v145, -v183
	v_fmac_f32_e32 v154, v146, v146
	v_fmac_f32_e32 v147, v143, v143
	s_waitcnt lgkmcnt(1)
	v_fma_f32 v167, v14, v167, -v192
	v_fma_f32 v145, v15, v169, -v193
	v_fmac_f32_e32 v149, v167, v167
	v_fmac_f32_e32 v148, v145, v145
	s_waitcnt lgkmcnt(0)
	v_fma_f32 v170, v16, v170, -v196
	v_fma_f32 v169, v17, v173, -v197
	v_fmac_f32_e32 v158, v170, v170
	v_fmac_f32_e32 v156, v169, v169
	ds_swizzle_b32 v196, v179 offset:swizzle(SWAP,1)
	ds_swizzle_b32 v197, v178 offset:swizzle(SWAP,1)
	ds_swizzle_b32 v198, v177 offset:swizzle(SWAP,1)
	ds_swizzle_b32 v199, v176 offset:swizzle(SWAP,1)
	ds_swizzle_b32 v200, v175 offset:swizzle(SWAP,1)
	ds_swizzle_b32 v201, v171 offset:swizzle(SWAP,1)
	ds_swizzle_b32 v206, v172 offset:swizzle(SWAP,1)
	ds_swizzle_b32 v207, v168 offset:swizzle(SWAP,1)
	ds_swizzle_b32 v208, v166 offset:swizzle(SWAP,1)
	ds_swizzle_b32 v209, v161 offset:swizzle(SWAP,1)
	ds_swizzle_b32 v210, v154 offset:swizzle(SWAP,1)
	s_waitcnt lgkmcnt(10)
	v_add_f32_e32 v180, v179, v196
	s_waitcnt lgkmcnt(9)
	v_add_f32_e32 v181, v178, v197
	s_waitcnt lgkmcnt(8)
	v_add_f32_e32 v182, v177, v198
	s_waitcnt lgkmcnt(7)
	v_add_f32_e32 v183, v176, v199
	s_waitcnt lgkmcnt(6)
	v_add_f32_e32 v184, v175, v200
	s_waitcnt lgkmcnt(5)
	v_add_f32_e32 v185, v171, v201
	ds_swizzle_b32 v211, v147 offset:swizzle(SWAP,1)
	ds_swizzle_b32 v212, v149 offset:swizzle(SWAP,1)
	ds_swizzle_b32 v213, v148 offset:swizzle(SWAP,1)
	ds_swizzle_b32 v214, v158 offset:swizzle(SWAP,1)
	ds_swizzle_b32 v215, v156 offset:swizzle(SWAP,1)
	s_waitcnt lgkmcnt(9)
	v_add_f32_e32 v186, v172, v206
	s_waitcnt lgkmcnt(8)
	v_add_f32_e32 v187, v168, v207
	s_waitcnt lgkmcnt(7)
	v_add_f32_e32 v188, v166, v208
	s_waitcnt lgkmcnt(6)
	v_add_f32_e32 v189, v161, v209
	s_waitcnt lgkmcnt(5)
	v_add_f32_e32 v190, v154, v210
	ds_swizzle_b32 v196, v180 offset:swizzle(SWAP,2)
	ds_swizzle_b32 v197, v181 offset:swizzle(SWAP,2)
	ds_swizzle_b32 v198, v182 offset:swizzle(SWAP,2)
	ds_swizzle_b32 v199, v183 offset:swizzle(SWAP,2)
	ds_swizzle_b32 v200, v184 offset:swizzle(SWAP,2)
	ds_swizzle_b32 v201, v185 offset:swizzle(SWAP,2)
	s_waitcnt lgkmcnt(10)
	v_add_f32_e32 v191, v147, v211
	s_waitcnt lgkmcnt(9)
	v_add_f32_e32 v192, v149, v212
	s_waitcnt lgkmcnt(8)
	v_add_f32_e32 v193, v148, v213
	s_waitcnt lgkmcnt(7)
	v_add_f32_e32 v194, v158, v214
	s_waitcnt lgkmcnt(6)
	v_add_f32_e32 v195, v156, v215
	ds_swizzle_b32 v206, v186 offset:swizzle(SWAP,2)
	ds_swizzle_b32 v207, v187 offset:swizzle(SWAP,2)
	ds_swizzle_b32 v208, v188 offset:swizzle(SWAP,2)
	ds_swizzle_b32 v209, v189 offset:swizzle(SWAP,2)
	ds_swizzle_b32 v210, v190 offset:swizzle(SWAP,2)
	s_waitcnt lgkmcnt(10)
	v_add_f32_e32 v180, v180, v196
	s_waitcnt lgkmcnt(9)
	v_add_f32_e32 v181, v181, v197
	s_waitcnt lgkmcnt(8)
	v_add_f32_e32 v182, v182, v198
	s_waitcnt lgkmcnt(7)
	v_add_f32_e32 v183, v183, v199
	s_waitcnt lgkmcnt(6)
	v_add_f32_e32 v184, v184, v200
	s_waitcnt lgkmcnt(5)
	v_add_f32_e32 v185, v185, v201
	ds_swizzle_b32 v211, v191 offset:swizzle(SWAP,2)
	ds_swizzle_b32 v212, v192 offset:swizzle(SWAP,2)
	ds_swizzle_b32 v213, v193 offset:swizzle(SWAP,2)
	ds_swizzle_b32 v214, v194 offset:swizzle(SWAP,2)
	ds_swizzle_b32 v215, v195 offset:swizzle(SWAP,2)
	s_waitcnt lgkmcnt(9)
	v_add_f32_e32 v186, v186, v206
	s_waitcnt lgkmcnt(8)
	v_add_f32_e32 v187, v187, v207
	s_waitcnt lgkmcnt(7)
	v_add_f32_e32 v188, v188, v208
	s_waitcnt lgkmcnt(6)
	v_add_f32_e32 v189, v189, v209
	s_waitcnt lgkmcnt(5)
	v_add_f32_e32 v190, v190, v210
	ds_swizzle_b32 v196, v180 offset:swizzle(SWAP,4)
	ds_swizzle_b32 v197, v181 offset:swizzle(SWAP,4)
	ds_swizzle_b32 v198, v182 offset:swizzle(SWAP,4)
	ds_swizzle_b32 v199, v183 offset:swizzle(SWAP,4)
	ds_swizzle_b32 v200, v184 offset:swizzle(SWAP,4)
	ds_swizzle_b32 v201, v185 offset:swizzle(SWAP,4)
	s_waitcnt lgkmcnt(10)
; template <bool FIXED>
; __device__ __forceinline__ void df_unit(LAS char* lds, bf16_t* QKV, const float* gsub, float lam, float post, int b, int h, int qb, int wave0, float mfix2) {
;     ...
;         for (int r = 0; r < 16; ++r) { float s = ssq[r]; s = xsum<1>(s); s = xsum<2>(s); s = xsum<4>(s); s = xsum<8>(s); s = xsum<16>(s);
;             ssq[r] = post * __builtin_amdgcn_rsqf(s * (1.0f / 256.0f) + EPS); }
	v_add_f32_e32 v191, v191, v211
	s_waitcnt lgkmcnt(9)
	v_add_f32_e32 v192, v192, v212
	s_waitcnt lgkmcnt(8)
	v_add_f32_e32 v193, v193, v213
	s_waitcnt lgkmcnt(7)
	v_add_f32_e32 v194, v194, v214
	s_waitcnt lgkmcnt(6)
	v_add_f32_e32 v195, v195, v215
	ds_swizzle_b32 v206, v186 offset:swizzle(SWAP,4)
	ds_swizzle_b32 v207, v187 offset:swizzle(SWAP,4)
	ds_swizzle_b32 v208, v188 offset:swizzle(SWAP,4)
	ds_swizzle_b32 v209, v189 offset:swizzle(SWAP,4)
	ds_swizzle_b32 v210, v190 offset:swizzle(SWAP,4)
	s_waitcnt lgkmcnt(10)
	v_add_f32_e32 v180, v180, v196
	s_waitcnt lgkmcnt(9)
	v_add_f32_e32 v181, v181, v197
	s_waitcnt lgkmcnt(8)
	v_add_f32_e32 v182, v182, v198
	s_waitcnt lgkmcnt(7)
	v_add_f32_e32 v183, v183, v199
	s_waitcnt lgkmcnt(6)
	v_add_f32_e32 v184, v184, v200
	s_waitcnt lgkmcnt(5)
	v_add_f32_e32 v185, v185, v201
	ds_swizzle_b32 v211, v191 offset:swizzle(SWAP,4)
	ds_swizzle_b32 v212, v192 offset:swizzle(SWAP,4)
	ds_swizzle_b32 v213, v193 offset:swizzle(SWAP,4)
	ds_swizzle_b32 v214, v194 offset:swizzle(SWAP,4)
	ds_swizzle_b32 v215, v195 offset:swizzle(SWAP,4)
	s_waitcnt lgkmcnt(9)
	v_add_f32_e32 v186, v186, v206
	s_waitcnt lgkmcnt(8)
	v_add_f32_e32 v187, v187, v207
	s_waitcnt lgkmcnt(7)
	v_add_f32_e32 v188, v188, v208
	s_waitcnt lgkmcnt(6)
	v_add_f32_e32 v189, v189, v209
	s_waitcnt lgkmcnt(5)
	v_add_f32_e32 v190, v190, v210
	ds_swizzle_b32 v196, v180 offset:swizzle(SWAP,8)
	ds_swizzle_b32 v197, v181 offset:swizzle(SWAP,8)
	ds_swizzle_b32 v198, v182 offset:swizzle(SWAP,8)
	ds_swizzle_b32 v199, v183 offset:swizzle(SWAP,8)
	ds_swizzle_b32 v200, v184 offset:swizzle(SWAP,8)
	ds_swizzle_b32 v201, v185 offset:swizzle(SWAP,8)
	s_waitcnt lgkmcnt(10)
	v_add_f32_e32 v191, v191, v211
	s_waitcnt lgkmcnt(9)
	v_add_f32_e32 v192, v192, v212
	s_waitcnt lgkmcnt(8)
	v_add_f32_e32 v193, v193, v213
	s_waitcnt lgkmcnt(7)
	v_add_f32_e32 v194, v194, v214
	s_waitcnt lgkmcnt(6)
	v_add_f32_e32 v195, v195, v215
	ds_swizzle_b32 v206, v186 offset:swizzle(SWAP,8)
	ds_swizzle_b32 v207, v187 offset:swizzle(SWAP,8)
	ds_swizzle_b32 v208, v188 offset:swizzle(SWAP,8)
	ds_swizzle_b32 v209, v189 offset:swizzle(SWAP,8)
	ds_swizzle_b32 v210, v190 offset:swizzle(SWAP,8)
	s_waitcnt lgkmcnt(10)
	v_add_f32_e32 v180, v180, v196
	s_waitcnt lgkmcnt(9)
	v_add_f32_e32 v181, v181, v197
	s_waitcnt lgkmcnt(8)
	v_add_f32_e32 v182, v182, v198
	s_waitcnt lgkmcnt(7)
	v_add_f32_e32 v183, v183, v199
	s_waitcnt lgkmcnt(6)
	v_add_f32_e32 v184, v184, v200
	s_waitcnt lgkmcnt(5)
	v_add_f32_e32 v185, v185, v201
	ds_swizzle_b32 v211, v191 offset:swizzle(SWAP,8)
	ds_swizzle_b32 v212, v192 offset:swizzle(SWAP,8)
	ds_swizzle_b32 v213, v193 offset:swizzle(SWAP,8)
	ds_swizzle_b32 v214, v194 offset:swizzle(SWAP,8)
	ds_swizzle_b32 v215, v195 offset:swizzle(SWAP,8)
	s_waitcnt lgkmcnt(9)
	v_add_f32_e32 v186, v186, v206
	s_waitcnt lgkmcnt(8)
	v_add_f32_e32 v187, v187, v207
	s_waitcnt lgkmcnt(7)
	v_add_f32_e32 v188, v188, v208
	s_waitcnt lgkmcnt(6)
	v_add_f32_e32 v189, v189, v209
	s_waitcnt lgkmcnt(5)
	v_add_f32_e32 v190, v190, v210
	ds_swizzle_b32 v196, v180 offset:swizzle(SWAP,16)
	ds_swizzle_b32 v197, v181 offset:swizzle(SWAP,16)
	ds_swizzle_b32 v198, v182 offset:swizzle(SWAP,16)
	ds_swizzle_b32 v199, v183 offset:swizzle(SWAP,16)
	ds_swizzle_b32 v200, v184 offset:swizzle(SWAP,16)
	ds_swizzle_b32 v201, v185 offset:swizzle(SWAP,16)
	s_waitcnt lgkmcnt(10)
	v_add_f32_e32 v191, v191, v211
	s_waitcnt lgkmcnt(9)
	v_add_f32_e32 v192, v192, v212
	s_waitcnt lgkmcnt(8)
	v_add_f32_e32 v193, v193, v213
	s_waitcnt lgkmcnt(7)
	v_add_f32_e32 v194, v194, v214
	s_waitcnt lgkmcnt(6)
	v_add_f32_e32 v195, v195, v215
	ds_swizzle_b32 v206, v186 offset:swizzle(SWAP,16)
	ds_swizzle_b32 v207, v187 offset:swizzle(SWAP,16)
	ds_swizzle_b32 v208, v188 offset:swizzle(SWAP,16)
	ds_swizzle_b32 v209, v189 offset:swizzle(SWAP,16)
	ds_swizzle_b32 v210, v190 offset:swizzle(SWAP,16)
	s_waitcnt lgkmcnt(10)
	v_add_f32_e32 v180, v180, v196
	s_waitcnt lgkmcnt(9)
	v_add_f32_e32 v181, v181, v197
	s_waitcnt lgkmcnt(8)
	v_add_f32_e32 v182, v182, v198
	s_waitcnt lgkmcnt(7)
	v_add_f32_e32 v183, v183, v199
	s_waitcnt lgkmcnt(6)
	v_add_f32_e32 v184, v184, v200
	s_waitcnt lgkmcnt(5)
	v_add_f32_e32 v185, v185, v201
	ds_swizzle_b32 v211, v191 offset:swizzle(SWAP,16)
	ds_swizzle_b32 v212, v192 offset:swizzle(SWAP,16)
	ds_swizzle_b32 v213, v193 offset:swizzle(SWAP,16)
	ds_swizzle_b32 v214, v194 offset:swizzle(SWAP,16)
	ds_swizzle_b32 v215, v195 offset:swizzle(SWAP,16)
	s_waitcnt lgkmcnt(9)
	v_add_f32_e32 v186, v186, v206
	s_waitcnt lgkmcnt(8)
	v_add_f32_e32 v187, v187, v207
	s_waitcnt lgkmcnt(7)
	v_add_f32_e32 v188, v188, v208
	s_waitcnt lgkmcnt(6)
	v_add_f32_e32 v189, v189, v209
	s_waitcnt lgkmcnt(5)
	v_add_f32_e32 v190, v190, v210
	s_waitcnt lgkmcnt(4)
	v_add_f32_e32 v191, v191, v211
	s_waitcnt lgkmcnt(3)
	v_add_f32_e32 v192, v192, v212
	s_waitcnt lgkmcnt(2)
	v_add_f32_e32 v193, v193, v213
	s_waitcnt lgkmcnt(1)
	v_add_f32_e32 v194, v194, v214
	s_waitcnt lgkmcnt(0)
; __device__ __forceinline__ int crow(int r, int hi) { return (r & 3) + 8 * (r >> 2) + 4 * hi; }
; __device__ __forceinline__ unsigned cvtpk(float lo, float hi) { unsigned r; asm volatile("v_cvt_pk_bf16_f32 %0, %1, %2" : "=v"(r) : "v"(lo), "v"(hi)); return r; }
; template <bool FIXED>
; __device__ __forceinline__ void df_unit(LAS char* lds, bf16_t* QKV, const float* gsub, float lam, float post, int b, int h, int qb, int wave0, float mfix2) {
;     ...
;         for (int r = 0; r < 16; ++r) { float s = ssq[r]; s = xsum<1>(s); s = xsum<2>(s); s = xsum<4>(s); s = xsum<8>(s); s = xsum<16>(s);
;             ssq[r] = post * __builtin_amdgcn_rsqf(s * (1.0f / 256.0f) + EPS); }
; #pragma unroll
;         for (int d = 0; d < 8; ++d) { const float g = gsub[d * 32 + r32];
; #pragma unroll
;             for (int r = 0; r < 16; ++r) *(unsigned short*)(rowsq + (size_t)crow(r, hi) * PITCH + d * 32 + r32) = (unsigned short)cvtpk(o[d][r] * ssq[r] * g, 0.f); }
	v_add_f32_e32 v195, v195, v215
	v_fmamk_f32 v180, v180, 0x3b800000, v223
	v_fmamk_f32 v181, v181, 0x3b800000, v223
	v_fmamk_f32 v182, v182, 0x3b800000, v223
	v_fmamk_f32 v183, v183, 0x3b800000, v223
	v_fmamk_f32 v184, v184, 0x3b800000, v223
	v_fmamk_f32 v185, v185, 0x3b800000, v223
	v_fmamk_f32 v186, v186, 0x3b800000, v223
	v_fmamk_f32 v187, v187, 0x3b800000, v223
	v_fmamk_f32 v188, v188, 0x3b800000, v223
	v_fmamk_f32 v189, v189, 0x3b800000, v223
	v_fmamk_f32 v190, v190, 0x3b800000, v223
	v_fmamk_f32 v191, v191, 0x3b800000, v223
	v_fmamk_f32 v192, v192, 0x3b800000, v223
	v_fmamk_f32 v193, v193, 0x3b800000, v223
	v_fmamk_f32 v194, v194, 0x3b800000, v223
	v_fmamk_f32 v195, v195, 0x3b800000, v223
	v_rsq_f32_e32 v180, v180
	v_rsq_f32_e32 v181, v181
	v_rsq_f32_e32 v182, v182
	v_rsq_f32_e32 v183, v183
	v_rsq_f32_e32 v184, v184
	v_rsq_f32_e32 v185, v185
	v_rsq_f32_e32 v186, v186
	v_rsq_f32_e32 v187, v187
	v_rsq_f32_e32 v188, v188
	v_rsq_f32_e32 v189, v189
	v_rsq_f32_e32 v190, v190
	v_rsq_f32_e32 v191, v191
	v_rsq_f32_e32 v192, v192
	v_rsq_f32_e32 v193, v193
	v_rsq_f32_e32 v194, v194
	v_rsq_f32_e32 v195, v195
	v_mul_f32_e32 v173, v232, v180
	v_mul_f32_e32 v174, v232, v181
	v_mul_f32_e32 v177, v232, v182
	v_mul_f32_e32 v176, v232, v183
	v_mul_f32_e32 v175, v232, v184
	v_mul_f32_e32 v171, v232, v185
	v_mul_f32_e32 v172, v232, v186
	v_mul_f32_e32 v168, v232, v187
	v_mul_f32_e32 v166, v232, v188
	v_mul_f32_e32 v161, v232, v189
	v_mul_f32_e32 v154, v232, v190
	v_mul_f32_e32 v147, v232, v191
	v_mul_f32_e32 v149, v232, v192
	v_mul_f32_e32 v148, v232, v193
	v_mul_f32_e32 v158, v232, v194
	v_mul_f32_e32 v156, v232, v195
	v_mul_f32_e32 v114, v114, v173
	v_lshlrev_b32_e32 v178, 2, v203
	global_load_dword v179, v178, s[68:69]
	v_mul_f32_e32 v98, v98, v174
	v_mul_f32_e32 v82, v82, v174
	v_mul_f32_e32 v66, v66, v174
	v_mul_f32_e32 v50, v50, v174
	v_mul_f32_e32 v34, v34, v174
	s_lshl_b32 s0, s27, 15
	v_lshlrev_b32_e32 v183, 11, v202
	v_lshl_add_u32 v180, v203, 1, v183
	v_add_u32_e32 v180, s0, v180
	v_lshl_add_u32 v181, v204, 4, s0
	v_mul_u32_u24_e32 v182, 0x3000, v202
	v_lshl_add_u32 v182, v203, 4, v182
	global_load_dword v184, v178, s[68:69] offset:128
	global_load_dword v185, v178, s[68:69] offset:256
	global_load_dword v186, v178, s[68:69] offset:384
	global_load_dword v187, v178, s[68:69] offset:512
	global_load_dword v188, v178, s[68:69] offset:640
	global_load_dword v189, v178, s[68:69] offset:768
	global_load_dword v190, v178, s[68:69] offset:896
	v_mul_f32_e32 v192, v135, v173
	v_mul_f32_e32 v194, v131, v174
	v_mul_f32_e32 v196, v132, v177
	v_mul_f32_e32 v198, v117, v176
	s_waitcnt vmcnt(0)
	v_mul_f32_e32 v192, v192, v179
	v_mul_f32_e32 v194, v194, v179
	v_mul_f32_e32 v196, v196, v179
	v_mul_f32_e32 v198, v198, v179
	v_cvt_pk_bf16_f32 v193, v192, v1
	v_cvt_pk_bf16_f32 v195, v194, v1
	v_cvt_pk_bf16_f32 v197, v196, v1
	v_cvt_pk_bf16_f32 v199, v198, v1
	ds_write_b16 v180, v193 offset:0
	ds_write_b16 v180, v195 offset:512
	ds_write_b16 v180, v197 offset:1024
	ds_write_b16 v180, v199 offset:1536
	v_mul_f32_e32 v192, v130, v175
	v_mul_f32_e32 v194, v115, v171
	v_mul_f32_e32 v196, v134, v172
	v_mul_f32_e32 v198, v119, v168
	v_mul_f32_e32 v192, v192, v179
	v_mul_f32_e32 v194, v194, v179
	v_mul_f32_e32 v196, v196, v179
	v_mul_f32_e32 v198, v198, v179
	v_cvt_pk_bf16_f32 v193, v192, v1
	v_cvt_pk_bf16_f32 v195, v194, v1
	v_cvt_pk_bf16_f32 v197, v196, v1
	v_cvt_pk_bf16_f32 v199, v198, v1
	ds_write_b16 v180, v193 offset:4096
	ds_write_b16 v180, v195 offset:4608
	ds_write_b16 v180, v197 offset:5120
	ds_write_b16 v180, v199 offset:5632
	v_mul_f32_e32 v192, v133, v166
	v_mul_f32_e32 v194, v120, v161
	v_mul_f32_e32 v196, v123, v154
	v_mul_f32_e32 v198, v118, v147
	v_mul_f32_e32 v192, v192, v179
	v_mul_f32_e32 v194, v194, v179
	v_mul_f32_e32 v196, v196, v179
	v_mul_f32_e32 v198, v198, v179
	v_cvt_pk_bf16_f32 v193, v192, v1
	v_cvt_pk_bf16_f32 v195, v194, v1
	v_cvt_pk_bf16_f32 v197, v196, v1
	v_cvt_pk_bf16_f32 v199, v198, v1
	ds_write_b16 v180, v193 offset:8192
	ds_write_b16 v180, v195 offset:8704
	ds_write_b16 v180, v197 offset:9216
	ds_write_b16 v180, v199 offset:9728
	v_mul_f32_e32 v192, v122, v149
	v_mul_f32_e32 v194, v116, v148
	v_mul_f32_e32 v196, v124, v158
	v_mul_f32_e32 v198, v121, v156
	v_mul_f32_e32 v192, v192, v179
	v_mul_f32_e32 v194, v194, v179
	v_mul_f32_e32 v196, v179, v196
	v_mul_f32_e32 v198, v179, v198
	v_cvt_pk_bf16_f32 v193, v192, v1
	v_cvt_pk_bf16_f32 v195, v194, v1
	v_cvt_pk_bf16_f32 v197, v196, v1
	v_cvt_pk_bf16_f32 v199, v198, v1
	ds_write_b16 v180, v193 offset:12288
	ds_write_b16 v180, v195 offset:12800
	ds_write_b16 v180, v197 offset:13312
	ds_write_b16 v180, v199 offset:13824
	v_mul_f32_e32 v196, v100, v177
	v_mul_f32_e32 v198, v99, v176
	v_mul_f32_e32 v192, v114, v184
	v_mul_f32_e32 v194, v98, v184
	v_mul_f32_e32 v196, v196, v184
	v_mul_f32_e32 v198, v198, v184
	v_cvt_pk_bf16_f32 v193, v192, v1
	v_cvt_pk_bf16_f32 v195, v194, v1
	v_cvt_pk_bf16_f32 v197, v196, v1
	v_cvt_pk_bf16_f32 v199, v198, v1
	ds_write_b16 v180, v193 offset:64
	ds_write_b16 v180, v195 offset:576
	ds_write_b16 v180, v197 offset:1088
	ds_write_b16 v180, v199 offset:1600
	v_mul_f32_e32 v192, v102, v175
	v_mul_f32_e32 v194, v101, v171
	v_mul_f32_e32 v196, v104, v172
	v_mul_f32_e32 v198, v103, v168
	v_mul_f32_e32 v192, v192, v184
	v_mul_f32_e32 v194, v194, v184
	v_mul_f32_e32 v196, v196, v184
	v_mul_f32_e32 v198, v198, v184
	v_cvt_pk_bf16_f32 v193, v192, v1
	v_cvt_pk_bf16_f32 v195, v194, v1
	v_cvt_pk_bf16_f32 v197, v196, v1
	v_cvt_pk_bf16_f32 v199, v198, v1
	ds_write_b16 v180, v193 offset:4160
	ds_write_b16 v180, v195 offset:4672
	ds_write_b16 v180, v197 offset:5184
; __device__ __forceinline__ int crow(int r, int hi) { return (r & 3) + 8 * (r >> 2) + 4 * hi; }
; __device__ __forceinline__ unsigned cvtpk(float lo, float hi) { unsigned r; asm volatile("v_cvt_pk_bf16_f32 %0, %1, %2" : "=v"(r) : "v"(lo), "v"(hi)); return r; }
; template <bool FIXED>
; __device__ __forceinline__ void df_unit(LAS char* lds, bf16_t* QKV, const float* gsub, float lam, float post, int b, int h, int qb, int wave0, float mfix2) {
;     ...
;         for (int d = 0; d < 8; ++d) { const float g = gsub[d * 32 + r32];
; #pragma unroll
;             for (int r = 0; r < 16; ++r) *(unsigned short*)(rowsq + (size_t)crow(r, hi) * PITCH + d * 32 + r32) = (unsigned short)cvtpk(o[d][r] * ssq[r] * g, 0.f); }
	ds_write_b16 v180, v199 offset:5696
	v_mul_f32_e32 v192, v106, v166
	v_mul_f32_e32 v194, v105, v161
	v_mul_f32_e32 v196, v108, v154
	v_mul_f32_e32 v198, v107, v147
	v_mul_f32_e32 v192, v192, v184
	v_mul_f32_e32 v194, v194, v184
	v_mul_f32_e32 v196, v196, v184
	v_mul_f32_e32 v198, v198, v184
	v_cvt_pk_bf16_f32 v193, v192, v1
	v_cvt_pk_bf16_f32 v195, v194, v1
	v_cvt_pk_bf16_f32 v197, v196, v1
	v_cvt_pk_bf16_f32 v199, v198, v1
	ds_write_b16 v180, v193 offset:8256
	ds_write_b16 v180, v195 offset:8768
	ds_write_b16 v180, v197 offset:9280
	ds_write_b16 v180, v199 offset:9792
	v_mul_f32_e32 v192, v110, v149
	v_mul_f32_e32 v194, v109, v148
	v_mul_f32_e32 v196, v112, v158
	v_mul_f32_e32 v198, v113, v156
	v_mul_f32_e32 v192, v192, v184
	v_mul_f32_e32 v194, v194, v184
	v_mul_f32_e32 v196, v196, v184
	v_mul_f32_e32 v198, v198, v184
	v_cvt_pk_bf16_f32 v193, v192, v1
	v_cvt_pk_bf16_f32 v195, v194, v1
	v_cvt_pk_bf16_f32 v197, v196, v1
	v_cvt_pk_bf16_f32 v199, v198, v1
	ds_write_b16 v180, v193 offset:12352
	ds_write_b16 v180, v195 offset:12864
	ds_write_b16 v180, v197 offset:13376
	ds_write_b16 v180, v199 offset:13888
	v_mul_f32_e32 v192, v111, v173
	v_mul_f32_e32 v196, v84, v177
	v_mul_f32_e32 v198, v83, v176
	v_mul_f32_e32 v192, v192, v185
	v_mul_f32_e32 v194, v82, v185
	v_mul_f32_e32 v196, v196, v185
	v_mul_f32_e32 v198, v198, v185
	v_cvt_pk_bf16_f32 v193, v192, v1
	v_cvt_pk_bf16_f32 v195, v194, v1
	v_cvt_pk_bf16_f32 v197, v196, v1
	v_cvt_pk_bf16_f32 v199, v198, v1
	ds_write_b16 v180, v193 offset:128
	ds_write_b16 v180, v195 offset:640
	ds_write_b16 v180, v197 offset:1152
	ds_write_b16 v180, v199 offset:1664
	v_mul_f32_e32 v192, v86, v175
	v_mul_f32_e32 v194, v85, v171
	v_mul_f32_e32 v196, v88, v172
	v_mul_f32_e32 v198, v87, v168
	v_mul_f32_e32 v192, v192, v185
	v_mul_f32_e32 v194, v194, v185
	v_mul_f32_e32 v196, v196, v185
	v_mul_f32_e32 v198, v198, v185
	v_cvt_pk_bf16_f32 v193, v192, v1
	v_cvt_pk_bf16_f32 v195, v194, v1
	v_cvt_pk_bf16_f32 v197, v196, v1
	v_cvt_pk_bf16_f32 v199, v198, v1
	ds_write_b16 v180, v193 offset:4224
	ds_write_b16 v180, v195 offset:4736
	ds_write_b16 v180, v197 offset:5248
	ds_write_b16 v180, v199 offset:5760
	v_mul_f32_e32 v192, v90, v166
	v_mul_f32_e32 v194, v89, v161
	v_mul_f32_e32 v196, v92, v154
	v_mul_f32_e32 v198, v91, v147
	v_mul_f32_e32 v192, v192, v185
	v_mul_f32_e32 v194, v194, v185
	v_mul_f32_e32 v196, v196, v185
	v_mul_f32_e32 v198, v198, v185
	v_cvt_pk_bf16_f32 v193, v192, v1
	v_cvt_pk_bf16_f32 v195, v194, v1
	v_cvt_pk_bf16_f32 v197, v196, v1
	v_cvt_pk_bf16_f32 v199, v198, v1
	ds_write_b16 v180, v193 offset:8320
	ds_write_b16 v180, v195 offset:8832
	ds_write_b16 v180, v197 offset:9344
	ds_write_b16 v180, v199 offset:9856
	v_mul_f32_e32 v192, v94, v149
	v_mul_f32_e32 v194, v93, v148
	v_mul_f32_e32 v196, v125, v158
	v_mul_f32_e32 v198, v96, v156
	v_mul_f32_e32 v192, v192, v185
	v_mul_f32_e32 v194, v194, v185
	v_mul_f32_e32 v196, v196, v185
	v_mul_f32_e32 v198, v198, v185
	v_cvt_pk_bf16_f32 v193, v192, v1
	v_cvt_pk_bf16_f32 v195, v194, v1
	v_cvt_pk_bf16_f32 v197, v196, v1
	v_cvt_pk_bf16_f32 v199, v198, v1
	ds_write_b16 v180, v193 offset:12416
	ds_write_b16 v180, v195 offset:12928
	ds_write_b16 v180, v197 offset:13440
	ds_write_b16 v180, v199 offset:13952
	v_mul_f32_e32 v192, v95, v173
	v_mul_f32_e32 v196, v68, v177
	v_mul_f32_e32 v198, v67, v176
	v_mul_f32_e32 v192, v192, v186
	v_mul_f32_e32 v194, v66, v186
	v_mul_f32_e32 v196, v196, v186
	v_mul_f32_e32 v198, v198, v186
	v_cvt_pk_bf16_f32 v193, v192, v1
	v_cvt_pk_bf16_f32 v195, v194, v1
	v_cvt_pk_bf16_f32 v197, v196, v1
	v_cvt_pk_bf16_f32 v199, v198, v1
	ds_write_b16 v180, v193 offset:192
	ds_write_b16 v180, v195 offset:704
	ds_write_b16 v180, v197 offset:1216
	ds_write_b16 v180, v199 offset:1728
	v_mul_f32_e32 v192, v70, v175
	v_mul_f32_e32 v194, v69, v171
	v_mul_f32_e32 v196, v72, v172
	v_mul_f32_e32 v198, v71, v168
	v_mul_f32_e32 v192, v192, v186
	v_mul_f32_e32 v194, v194, v186
	v_mul_f32_e32 v196, v196, v186
	v_mul_f32_e32 v198, v198, v186
	v_cvt_pk_bf16_f32 v193, v192, v1
	v_cvt_pk_bf16_f32 v195, v194, v1
	v_cvt_pk_bf16_f32 v197, v196, v1
	v_cvt_pk_bf16_f32 v199, v198, v1
	ds_write_b16 v180, v193 offset:4288
	ds_write_b16 v180, v195 offset:4800
	ds_write_b16 v180, v197 offset:5312
	ds_write_b16 v180, v199 offset:5824
	v_mul_f32_e32 v192, v74, v166
	v_mul_f32_e32 v194, v73, v161
	v_mul_f32_e32 v196, v76, v154
	v_mul_f32_e32 v198, v75, v147
	v_mul_f32_e32 v192, v192, v186
	v_mul_f32_e32 v194, v194, v186
	v_mul_f32_e32 v196, v196, v186
	v_mul_f32_e32 v198, v198, v186
	v_cvt_pk_bf16_f32 v193, v192, v1
	v_cvt_pk_bf16_f32 v195, v194, v1
	v_cvt_pk_bf16_f32 v197, v196, v1
	v_cvt_pk_bf16_f32 v199, v198, v1
	ds_write_b16 v180, v193 offset:8384
	ds_write_b16 v180, v195 offset:8896
	ds_write_b16 v180, v197 offset:9408
	ds_write_b16 v180, v199 offset:9920
	v_mul_f32_e32 v192, v78, v149
	v_mul_f32_e32 v194, v77, v148
	v_mul_f32_e32 v196, v97, v158
	v_mul_f32_e32 v198, v80, v156
	v_mul_f32_e32 v192, v192, v186
	v_mul_f32_e32 v194, v194, v186
	v_mul_f32_e32 v196, v196, v186
	v_mul_f32_e32 v198, v198, v186
	v_cvt_pk_bf16_f32 v193, v192, v1
	v_cvt_pk_bf16_f32 v195, v194, v1
	v_cvt_pk_bf16_f32 v197, v196, v1
	v_cvt_pk_bf16_f32 v199, v198, v1
	ds_write_b16 v180, v193 offset:12480
	ds_write_b16 v180, v195 offset:12992
	ds_write_b16 v180, v197 offset:13504
	ds_write_b16 v180, v199 offset:14016
	v_mul_f32_e32 v192, v79, v173
	v_mul_f32_e32 v196, v52, v177
	v_mul_f32_e32 v198, v51, v176
	v_mul_f32_e32 v192, v192, v187
	v_mul_f32_e32 v194, v50, v187
	v_mul_f32_e32 v196, v196, v187
	v_mul_f32_e32 v198, v198, v187
	v_cvt_pk_bf16_f32 v193, v192, v1
	v_cvt_pk_bf16_f32 v195, v194, v1
; __device__ __forceinline__ int crow(int r, int hi) { return (r & 3) + 8 * (r >> 2) + 4 * hi; }
; __device__ __forceinline__ unsigned cvtpk(float lo, float hi) { unsigned r; asm volatile("v_cvt_pk_bf16_f32 %0, %1, %2" : "=v"(r) : "v"(lo), "v"(hi)); return r; }
; template <bool FIXED>
; __device__ __forceinline__ void df_unit(LAS char* lds, bf16_t* QKV, const float* gsub, float lam, float post, int b, int h, int qb, int wave0, float mfix2) {
;     ...
;         for (int d = 0; d < 8; ++d) { const float g = gsub[d * 32 + r32];
; #pragma unroll
;             for (int r = 0; r < 16; ++r) *(unsigned short*)(rowsq + (size_t)crow(r, hi) * PITCH + d * 32 + r32) = (unsigned short)cvtpk(o[d][r] * ssq[r] * g, 0.f); }
	v_cvt_pk_bf16_f32 v197, v196, v1
	v_cvt_pk_bf16_f32 v199, v198, v1
	ds_write_b16 v180, v193 offset:256
	ds_write_b16 v180, v195 offset:768
	ds_write_b16 v180, v197 offset:1280
	ds_write_b16 v180, v199 offset:1792
	v_mul_f32_e32 v192, v54, v175
	v_mul_f32_e32 v194, v53, v171
	v_mul_f32_e32 v196, v56, v172
	v_mul_f32_e32 v198, v55, v168
	v_mul_f32_e32 v192, v192, v187
	v_mul_f32_e32 v194, v194, v187
	v_mul_f32_e32 v196, v196, v187
	v_mul_f32_e32 v198, v198, v187
	v_cvt_pk_bf16_f32 v193, v192, v1
	v_cvt_pk_bf16_f32 v195, v194, v1
	v_cvt_pk_bf16_f32 v197, v196, v1
	v_cvt_pk_bf16_f32 v199, v198, v1
	ds_write_b16 v180, v193 offset:4352
	ds_write_b16 v180, v195 offset:4864
	ds_write_b16 v180, v197 offset:5376
	ds_write_b16 v180, v199 offset:5888
	v_mul_f32_e32 v192, v58, v166
	v_mul_f32_e32 v194, v57, v161
	v_mul_f32_e32 v196, v60, v154
	v_mul_f32_e32 v198, v59, v147
	v_mul_f32_e32 v192, v192, v187
	v_mul_f32_e32 v194, v194, v187
	v_mul_f32_e32 v196, v196, v187
	v_mul_f32_e32 v198, v198, v187
	v_cvt_pk_bf16_f32 v193, v192, v1
	v_cvt_pk_bf16_f32 v195, v194, v1
	v_cvt_pk_bf16_f32 v197, v196, v1
	v_cvt_pk_bf16_f32 v199, v198, v1
	ds_write_b16 v180, v193 offset:8448
	ds_write_b16 v180, v195 offset:8960
	ds_write_b16 v180, v197 offset:9472
	ds_write_b16 v180, v199 offset:9984
	v_mul_f32_e32 v192, v62, v149
	v_mul_f32_e32 v194, v61, v148
	v_mul_f32_e32 v196, v81, v158
	v_mul_f32_e32 v198, v64, v156
	v_mul_f32_e32 v192, v192, v187
	v_mul_f32_e32 v194, v194, v187
	v_mul_f32_e32 v196, v196, v187
	v_mul_f32_e32 v198, v198, v187
	v_cvt_pk_bf16_f32 v193, v192, v1
	v_cvt_pk_bf16_f32 v195, v194, v1
	v_cvt_pk_bf16_f32 v197, v196, v1
	v_cvt_pk_bf16_f32 v199, v198, v1
	ds_write_b16 v180, v193 offset:12544
	ds_write_b16 v180, v195 offset:13056
	ds_write_b16 v180, v197 offset:13568
	ds_write_b16 v180, v199 offset:14080
	v_mul_f32_e32 v192, v63, v173
	v_mul_f32_e32 v196, v36, v177
	v_mul_f32_e32 v198, v35, v176
	v_mul_f32_e32 v192, v192, v188
	v_mul_f32_e32 v194, v34, v188
	v_mul_f32_e32 v196, v196, v188
	v_mul_f32_e32 v198, v198, v188
	v_cvt_pk_bf16_f32 v193, v192, v1
	v_cvt_pk_bf16_f32 v195, v194, v1
	v_cvt_pk_bf16_f32 v197, v196, v1
	v_cvt_pk_bf16_f32 v199, v198, v1
	ds_write_b16 v180, v193 offset:320
	ds_write_b16 v180, v195 offset:832
	ds_write_b16 v180, v197 offset:1344
	ds_write_b16 v180, v199 offset:1856
	v_mul_f32_e32 v192, v38, v175
	v_mul_f32_e32 v194, v37, v171
	v_mul_f32_e32 v196, v40, v172
	v_mul_f32_e32 v198, v39, v168
	v_mul_f32_e32 v192, v192, v188
	v_mul_f32_e32 v194, v194, v188
	v_mul_f32_e32 v196, v196, v188
	v_mul_f32_e32 v198, v198, v188
	v_cvt_pk_bf16_f32 v193, v192, v1
	v_cvt_pk_bf16_f32 v195, v194, v1
	v_cvt_pk_bf16_f32 v197, v196, v1
	v_cvt_pk_bf16_f32 v199, v198, v1
	ds_write_b16 v180, v193 offset:4416
	ds_write_b16 v180, v195 offset:4928
	ds_write_b16 v180, v197 offset:5440
	ds_write_b16 v180, v199 offset:5952
	v_mul_f32_e32 v192, v42, v166
	v_mul_f32_e32 v194, v41, v161
	v_mul_f32_e32 v196, v44, v154
	v_mul_f32_e32 v198, v43, v147
	v_mul_f32_e32 v192, v192, v188
	v_mul_f32_e32 v194, v194, v188
	v_mul_f32_e32 v196, v196, v188
	v_mul_f32_e32 v198, v198, v188
	v_cvt_pk_bf16_f32 v193, v192, v1
	v_cvt_pk_bf16_f32 v195, v194, v1
	v_cvt_pk_bf16_f32 v197, v196, v1
	v_cvt_pk_bf16_f32 v199, v198, v1
	ds_write_b16 v180, v193 offset:8512
	ds_write_b16 v180, v195 offset:9024
	ds_write_b16 v180, v197 offset:9536
	ds_write_b16 v180, v199 offset:10048
	v_mul_f32_e32 v192, v46, v149
	v_mul_f32_e32 v194, v45, v148
	v_mul_f32_e32 v196, v65, v158
	v_mul_f32_e32 v198, v49, v156
	v_mul_f32_e32 v192, v192, v188
	v_mul_f32_e32 v194, v194, v188
	v_mul_f32_e32 v196, v196, v188
	v_mul_f32_e32 v198, v198, v188
	v_cvt_pk_bf16_f32 v193, v192, v1
	v_cvt_pk_bf16_f32 v195, v194, v1
	v_cvt_pk_bf16_f32 v197, v196, v1
	v_cvt_pk_bf16_f32 v199, v198, v1
	ds_write_b16 v180, v193 offset:12608
	ds_write_b16 v180, v195 offset:13120
	ds_write_b16 v180, v197 offset:13632
	ds_write_b16 v180, v199 offset:14144
	v_mul_f32_e32 v192, v48, v173
	v_mul_f32_e32 v194, v47, v174
	v_mul_f32_e32 v196, v127, v177
	v_mul_f32_e32 v198, v126, v176
	v_mul_f32_e32 v192, v192, v189
	v_mul_f32_e32 v194, v194, v189
	v_mul_f32_e32 v196, v196, v189
	v_mul_f32_e32 v198, v198, v189
	v_cvt_pk_bf16_f32 v193, v192, v1
	v_cvt_pk_bf16_f32 v195, v194, v1
	v_cvt_pk_bf16_f32 v197, v196, v1
	v_cvt_pk_bf16_f32 v199, v198, v1
	ds_write_b16 v180, v193 offset:384
	ds_write_b16 v180, v195 offset:896
	ds_write_b16 v180, v197 offset:1408
	ds_write_b16 v180, v199 offset:1920
	v_mul_f32_e32 v192, v129, v175
	v_mul_f32_e32 v194, v128, v171
	v_mul_f32_e32 v196, v151, v172
	v_mul_f32_e32 v198, v150, v168
	v_mul_f32_e32 v192, v192, v189
	v_mul_f32_e32 v194, v194, v189
	v_mul_f32_e32 v196, v196, v189
	v_mul_f32_e32 v198, v198, v189
	v_cvt_pk_bf16_f32 v193, v192, v1
	v_cvt_pk_bf16_f32 v195, v194, v1
	v_cvt_pk_bf16_f32 v197, v196, v1
	v_cvt_pk_bf16_f32 v199, v198, v1
	ds_write_b16 v180, v193 offset:4480
	ds_write_b16 v180, v195 offset:4992
	ds_write_b16 v180, v197 offset:5504
	ds_write_b16 v180, v199 offset:6016
	v_mul_f32_e32 v192, v153, v166
	v_mul_f32_e32 v194, v152, v161
	v_mul_f32_e32 v196, v157, v154
	v_mul_f32_e32 v198, v155, v147
	v_mul_f32_e32 v192, v192, v189
	v_mul_f32_e32 v194, v194, v189
	v_mul_f32_e32 v196, v196, v189
	v_mul_f32_e32 v198, v198, v189
	v_cvt_pk_bf16_f32 v193, v192, v1
; __device__ __forceinline__ int crow(int r, int hi) { return (r & 3) + 8 * (r >> 2) + 4 * hi; }
; __device__ __forceinline__ unsigned cvtpk(float lo, float hi) { unsigned r; asm volatile("v_cvt_pk_bf16_f32 %0, %1, %2" : "=v"(r) : "v"(lo), "v"(hi)); return r; }
; template <bool FIXED>
; __device__ __forceinline__ void df_unit(LAS char* lds, bf16_t* QKV, const float* gsub, float lam, float post, int b, int h, int qb, int wave0, float mfix2) {
;     ...
;         for (int d = 0; d < 8; ++d) { const float g = gsub[d * 32 + r32];
; #pragma unroll
;             for (int r = 0; r < 16; ++r) *(unsigned short*)(rowsq + (size_t)crow(r, hi) * PITCH + d * 32 + r32) = (unsigned short)cvtpk(o[d][r] * ssq[r] * g, 0.f); }
	v_cvt_pk_bf16_f32 v195, v194, v1
	v_cvt_pk_bf16_f32 v197, v196, v1
	v_cvt_pk_bf16_f32 v199, v198, v1
	ds_write_b16 v180, v193 offset:8576
	ds_write_b16 v180, v195 offset:9088
	ds_write_b16 v180, v197 offset:9600
	ds_write_b16 v180, v199 offset:10112
	v_mul_f32_e32 v192, v160, v149
	v_mul_f32_e32 v194, v159, v148
	v_mul_f32_e32 v196, v164, v158
	v_mul_f32_e32 v198, v163, v156
	v_mul_f32_e32 v192, v192, v189
	v_mul_f32_e32 v194, v194, v189
	v_mul_f32_e32 v196, v196, v189
	v_mul_f32_e32 v198, v198, v189
	v_cvt_pk_bf16_f32 v193, v192, v1
	v_cvt_pk_bf16_f32 v195, v194, v1
	v_cvt_pk_bf16_f32 v197, v196, v1
	v_cvt_pk_bf16_f32 v199, v198, v1
	ds_write_b16 v180, v193 offset:12672
	ds_write_b16 v180, v195 offset:13184
	ds_write_b16 v180, v197 offset:13696
	ds_write_b16 v180, v199 offset:14208
	v_mul_f32_e32 v192, v162, v173
	v_mul_f32_e32 v194, v136, v174
	v_mul_f32_e32 v196, v165, v177
	v_mul_f32_e32 v198, v137, v176
	v_mul_f32_e32 v192, v192, v190
	v_mul_f32_e32 v194, v194, v190
	v_mul_f32_e32 v196, v196, v190
	v_mul_f32_e32 v198, v198, v190
	v_cvt_pk_bf16_f32 v193, v192, v1
	v_cvt_pk_bf16_f32 v195, v194, v1
	v_cvt_pk_bf16_f32 v197, v196, v1
	v_cvt_pk_bf16_f32 v199, v198, v1
	ds_write_b16 v180, v193 offset:448
	ds_write_b16 v180, v195 offset:960
	ds_write_b16 v180, v197 offset:1472
	ds_write_b16 v180, v199 offset:1984
	v_mul_f32_e32 v192, v139, v175
	v_mul_f32_e32 v194, v138, v171
	v_mul_f32_e32 v196, v141, v172
	v_mul_f32_e32 v198, v140, v168
	v_mul_f32_e32 v192, v192, v190
	v_mul_f32_e32 v194, v194, v190
	v_mul_f32_e32 v196, v196, v190
	v_mul_f32_e32 v198, v198, v190
	v_cvt_pk_bf16_f32 v193, v192, v1
	v_cvt_pk_bf16_f32 v195, v194, v1
	v_cvt_pk_bf16_f32 v197, v196, v1
	v_cvt_pk_bf16_f32 v199, v198, v1
	ds_write_b16 v180, v193 offset:4544
	ds_write_b16 v180, v195 offset:5056
	ds_write_b16 v180, v197 offset:5568
	ds_write_b16 v180, v199 offset:6080
	v_mul_f32_e32 v192, v144, v166
	v_mul_f32_e32 v194, v142, v161
	v_mul_f32_e32 v196, v146, v154
	v_mul_f32_e32 v198, v143, v147
	v_mul_f32_e32 v192, v192, v190
	v_mul_f32_e32 v194, v194, v190
	v_mul_f32_e32 v196, v196, v190
	v_mul_f32_e32 v198, v198, v190
	v_cvt_pk_bf16_f32 v193, v192, v1
	v_cvt_pk_bf16_f32 v195, v194, v1
	v_cvt_pk_bf16_f32 v197, v196, v1
	v_cvt_pk_bf16_f32 v199, v198, v1
	ds_write_b16 v180, v193 offset:8640
	ds_write_b16 v180, v195 offset:9152
	ds_write_b16 v180, v197 offset:9664
	ds_write_b16 v180, v199 offset:10176
	v_mul_f32_e32 v192, v167, v149
	v_mul_f32_e32 v194, v145, v148
	v_mul_f32_e32 v196, v170, v158
	v_mul_f32_e32 v198, v169, v156
	v_mul_f32_e32 v192, v192, v190
	v_mul_f32_e32 v194, v194, v190
	v_mul_f32_e32 v196, v196, v190
	v_mul_f32_e32 v198, v198, v190
	v_cvt_pk_bf16_f32 v193, v192, v1
	v_cvt_pk_bf16_f32 v195, v194, v1
	v_cvt_pk_bf16_f32 v197, v196, v1
	v_cvt_pk_bf16_f32 v199, v198, v1
	ds_write_b16 v180, v193 offset:12736
	ds_write_b16 v180, v195 offset:13248
	ds_write_b16 v180, v197 offset:13760
	ds_write_b16 v180, v199 offset:14272
	s_waitcnt vmcnt(0) lgkmcnt(0)
	ds_read_b128 v[184:187], v181 offset:0
	ds_read_b128 v[188:191], v181 offset:1024
	ds_read_b128 v[192:195], v181 offset:2048
	ds_read_b128 v[196:199], v181 offset:3072
	ds_read_b128 v[206:209], v181 offset:4096
	s_waitcnt lgkmcnt(4)
	global_store_dwordx4 v182, v[184:187], s[8:9]
	v_add_u32_e32 v182, 0x6000, v182
	ds_read_b128 v[210:213], v181 offset:5120
	s_waitcnt lgkmcnt(4)
	global_store_dwordx4 v182, v[188:191], s[8:9]
	v_add_u32_e32 v182, 0x6000, v182
	ds_read_b128 v[234:237], v181 offset:6144
	s_waitcnt lgkmcnt(4)
	global_store_dwordx4 v182, v[192:195], s[8:9]
	v_add_u32_e32 v182, 0x6000, v182
	ds_read_b128 v[238:241], v181 offset:7168
	s_waitcnt lgkmcnt(4)
	global_store_dwordx4 v182, v[196:199], s[8:9]
	v_add_u32_e32 v182, 0x6000, v182
	ds_read_b128 v[242:245], v181 offset:8192
	s_waitcnt lgkmcnt(4)
	global_store_dwordx4 v182, v[206:209], s[8:9]
	v_add_u32_e32 v182, 0x6000, v182
	ds_read_b128 v[246:249], v181 offset:9216
	s_waitcnt lgkmcnt(4)
	global_store_dwordx4 v182, v[210:213], s[8:9]
	v_add_u32_e32 v182, 0x6000, v182
	ds_read_b128 v[184:187], v181 offset:10240
	s_waitcnt lgkmcnt(4)
	global_store_dwordx4 v182, v[234:237], s[8:9]
	v_add_u32_e32 v182, 0x6000, v182
	ds_read_b128 v[188:191], v181 offset:11264
	s_waitcnt lgkmcnt(4)
	global_store_dwordx4 v182, v[238:241], s[8:9]
	v_add_u32_e32 v182, 0x6000, v182
	ds_read_b128 v[192:195], v181 offset:12288
	s_waitcnt lgkmcnt(4)
	global_store_dwordx4 v182, v[242:245], s[8:9]
	v_add_u32_e32 v182, 0x6000, v182
	ds_read_b128 v[196:199], v181 offset:13312
	s_waitcnt lgkmcnt(4)
	global_store_dwordx4 v182, v[246:249], s[8:9]
	v_add_u32_e32 v182, 0x6000, v182
	ds_read_b128 v[206:209], v181 offset:14336
	s_waitcnt lgkmcnt(4)
	global_store_dwordx4 v182, v[184:187], s[8:9]
	v_add_u32_e32 v182, 0x6000, v182
	ds_read_b128 v[210:213], v181 offset:15360
	s_waitcnt lgkmcnt(4)
	global_store_dwordx4 v182, v[188:191], s[8:9]
	v_add_u32_e32 v182, 0x6000, v182
	s_waitcnt lgkmcnt(3)
	global_store_dwordx4 v182, v[192:195], s[8:9]
	v_add_u32_e32 v182, 0x6000, v182
	s_waitcnt lgkmcnt(2)
	global_store_dwordx4 v182, v[196:199], s[8:9]
	v_add_u32_e32 v182, 0x6000, v182
	s_waitcnt lgkmcnt(1)
	global_store_dwordx4 v182, v[206:209], s[8:9]
	v_add_u32_e32 v182, 0x6000, v182
	s_waitcnt lgkmcnt(0)
	global_store_dwordx4 v182, v[210:213], s[8:9]
